# v3: v1 + mid-iteration barrier, LDS-DMA of k-tile kt+2 issued 1.5 iterations ahead (2 stages)
# speedup vs baseline: 1.0128x; 1.0128x over previous
.LBB0_104:
	v_mov_b32_e32 v1, v168
	v_readlane_b32 s52, v254, 48
	v_readfirstlane_b32 s2, v1
	s_lshl_b32 s3, s2, 5
	s_lshl_b32 s2, s2, 6
	v_lshrrev_b32_e32 v3, 4, v1
	v_and_b32_e32 v4, 7, v1
	s_and_b32 s3, s3, 0xfffff000
	v_lshlrev_b32_e32 v1, 6, v1
	s_and_b32 s2, s2, 0x1000
	v_readlane_b32 s56, v254, 52
	v_bitop3_b32 v3, v3, v4, 3 bitop3:0x6c
	v_and_b32_e32 v1, 0x3c0, v1
	v_readlane_b32 s57, v254, 53
	s_add_u32 s36, s56, s21
	v_lshlrev_b32_e32 v69, 3, v3
	s_waitcnt vmcnt(0)
	v_or_b32_e32 v3, s3, v1
	v_or_b32_e32 v4, s2, v1
	s_addc_u32 s37, s57, s20
	s_lshl_b64 s[2:3], s[30:31], 1
	s_add_u32 s40, s56, s2
	s_waitcnt lgkmcnt(0)
	v_mov_b32_e32 v32, 0
	v_xor_b32_e32 v1, 32, v69
	s_addc_u32 s41, s57, s3
	s_mov_b64 s[42:43], 0
	s_mov_b32 s51, 0
	v_lshlrev_b32_e32 v3, 1, v3
	v_lshlrev_b32_e32 v68, 1, v4
	v_mov_b32_e32 v33, v32
	v_mov_b32_e32 v34, v32
	v_mov_b32_e32 v35, v32
	v_mov_b32_e32 v48, v32
	v_mov_b32_e32 v49, v32
	v_mov_b32_e32 v50, v32
	v_mov_b32_e32 v51, v32
	v_mov_b32_e32 v4, v32
	v_mov_b32_e32 v5, v32
	v_mov_b32_e32 v6, v32
	v_mov_b32_e32 v7, v32
	v_mov_b32_e32 v8, v32
	v_mov_b32_e32 v9, v32
	v_mov_b32_e32 v10, v32
	v_mov_b32_e32 v11, v32
	v_mov_b32_e32 v12, v32
	v_mov_b32_e32 v13, v32
	v_mov_b32_e32 v14, v32
	v_mov_b32_e32 v15, v32
	v_mov_b32_e32 v16, v32
	v_mov_b32_e32 v17, v32
	v_mov_b32_e32 v18, v32
	v_mov_b32_e32 v19, v32
	v_mov_b32_e32 v20, v32
	v_mov_b32_e32 v21, v32
	v_mov_b32_e32 v22, v32
	v_mov_b32_e32 v23, v32
	v_mov_b32_e32 v24, v32
	v_mov_b32_e32 v25, v32
	v_mov_b32_e32 v26, v32
	v_mov_b32_e32 v27, v32
	v_mov_b32_e32 v28, v32
	v_mov_b32_e32 v29, v32
	v_mov_b32_e32 v30, v32
	v_mov_b32_e32 v31, v32
	v_mov_b32_e32 v36, v32
	v_mov_b32_e32 v37, v32
	v_mov_b32_e32 v38, v32
	v_mov_b32_e32 v39, v32
	v_mov_b32_e32 v40, v32
	v_mov_b32_e32 v41, v32
	v_mov_b32_e32 v42, v32
	v_mov_b32_e32 v43, v32
	v_mov_b32_e32 v44, v32
	v_mov_b32_e32 v45, v32
	v_mov_b32_e32 v46, v32
	v_mov_b32_e32 v47, v32
	v_mov_b32_e32 v52, v32
	v_mov_b32_e32 v53, v32
	v_mov_b32_e32 v54, v32
	v_mov_b32_e32 v55, v32
	v_mov_b32_e32 v56, v32
	v_mov_b32_e32 v57, v32
	v_mov_b32_e32 v58, v32
	v_mov_b32_e32 v59, v32
	v_mov_b32_e32 v60, v32
	v_mov_b32_e32 v61, v32
	v_mov_b32_e32 v62, v32
	v_mov_b32_e32 v63, v32
	v_mov_b32_e32 v64, v32
	v_mov_b32_e32 v65, v32
	v_mov_b32_e32 v66, v32
	v_mov_b32_e32 v67, v32
	s_mov_b64 s[18:19], 0x1390080
	s_waitcnt vmcnt(0) lgkmcnt(0)
	s_barrier
	v_readlane_b32 s53, v254, 49
	v_readlane_b32 s54, v254, 50
	v_readlane_b32 s55, v254, 51
	v_readlane_b32 s58, v254, 54
	v_readlane_b32 s59, v254, 55
	v_lshlrev_b32_e32 v86, 1, v69
	v_add_u32_e32 v160, v3, v86
	v_add_u32_e32 v162, v68, v86
	v_lshlrev_b32_e32 v86, 1, v1
	v_add_u32_e32 v161, v3, v86
	v_add_u32_e32 v163, v68, v86
	v_lshrrev_b32_e32 v87, 3, v168
	v_xor_b32_e32 v86, v87, v168
	v_and_b32_e32 v86, 7, v86
	v_lshlrev_b32_e32 v86, 4, v86
	s_movk_i32 s35, 0x1600
	v_mad_u32_u24 v164, v87, s35, v86
	v_add_u32_e32 v165, 0x2c000, v164
	v_add_u32_e32 v166, 0x58000, v164
	v_add_u32_e32 v167, 0x84000, v164
	s_add_u32 s52, s36, 0x1390080
	s_addc_u32 s53, s37, 0
	s_add_u32 s54, s40, 0xf4b0080
	s_addc_u32 s55, s41, 0
	v_readfirstlane_b32 s35, v168
	s_lshl_b32 s35, s35, 4
	s_or_b32 s35, s35, 0x8000
	s_mov_b32 m0, s35
	s_nop 0
	global_load_lds_dwordx4 v164, s[52:53]
	s_add_u32 m0, s35, 0x1000
	s_nop 0
	global_load_lds_dwordx4 v165, s[52:53]
	s_add_u32 m0, s35, 0x2000
	s_nop 0
	global_load_lds_dwordx4 v166, s[52:53]
	s_add_u32 m0, s35, 0x3000
	s_nop 0
	global_load_lds_dwordx4 v167, s[52:53]
	s_add_u32 m0, s35, 0x4000
	s_nop 0
	global_load_lds_dwordx4 v164, s[54:55]
	s_add_u32 m0, s35, 0x5000
	s_nop 0
	global_load_lds_dwordx4 v165, s[54:55]
	s_add_u32 m0, s35, 0x6000
	s_nop 0
	global_load_lds_dwordx4 v166, s[54:55]
	s_add_u32 m0, s35, 0x7000
	s_nop 0
	global_load_lds_dwordx4 v167, s[54:55]
	s_add_u32 s52, s52, 0x80
	s_addc_u32 s53, s53, 0
	s_add_u32 s54, s54, 0x80
	s_addc_u32 s55, s55, 0
	s_xor_b32 s35, s35, 0x8000
.LBB0_105:
	s_waitcnt vmcnt(8)
	s_barrier
	ds_read_b128 v[70:73], v160
	ds_read_b128 v[74:77], v160 offset:2048
	ds_read_b128 v[78:81], v160 offset:4096
	ds_read_b128 v[82:85], v160 offset:6144
	ds_read_b128 v[112:115], v162 offset:16384
	ds_read_b128 v[116:119], v162 offset:18432
	ds_read_b128 v[120:123], v162 offset:20480
	ds_read_b128 v[124:127], v162 offset:22528
	ds_read_b128 v[128:131], v161
	ds_read_b128 v[132:135], v161 offset:2048
	ds_read_b128 v[136:139], v161 offset:4096
	ds_read_b128 v[140:143], v161 offset:6144
	ds_read_b128 v[144:147], v163 offset:16384
	ds_read_b128 v[148:151], v163 offset:18432
	ds_read_b128 v[152:155], v163 offset:20480
	s_waitcnt lgkmcnt(10)
	v_mfma_f32_16x16x32_bf16 v[64:67], v[112:115], v[70:73], v[64:67]
	v_mfma_f32_16x16x32_bf16 v[60:63], v[112:115], v[74:77], v[60:63]
	v_mfma_f32_16x16x32_bf16 v[56:59], v[112:115], v[78:81], v[56:59]
	v_mfma_f32_16x16x32_bf16 v[52:55], v[112:115], v[82:85], v[52:55]
	ds_read_b128 v[156:159], v163 offset:22528
	s_waitcnt lgkmcnt(10)
	v_mfma_f32_16x16x32_bf16 v[44:47], v[116:119], v[70:73], v[44:47]
	v_mfma_f32_16x16x32_bf16 v[40:43], v[116:119], v[74:77], v[40:43]
	v_mfma_f32_16x16x32_bf16 v[36:39], v[116:119], v[78:81], v[36:39]
	v_mfma_f32_16x16x32_bf16 v[28:31], v[116:119], v[82:85], v[28:31]
	v_xor_b32_e32 v160, 0x8000, v160
	v_xor_b32_e32 v162, 0x8000, v162
	s_waitcnt lgkmcnt(9)
	v_mfma_f32_16x16x32_bf16 v[24:27], v[120:123], v[70:73], v[24:27]
	v_mfma_f32_16x16x32_bf16 v[20:23], v[120:123], v[74:77], v[20:23]
	v_mfma_f32_16x16x32_bf16 v[16:19], v[120:123], v[78:81], v[16:19]
	v_mfma_f32_16x16x32_bf16 v[12:15], v[120:123], v[82:85], v[12:15]
	v_xor_b32_e32 v161, 0x8000, v161
	v_xor_b32_e32 v163, 0x8000, v163
	s_waitcnt lgkmcnt(8)
	v_mfma_f32_16x16x32_bf16 v[8:11], v[124:127], v[70:73], v[8:11]
	v_mfma_f32_16x16x32_bf16 v[4:7], v[124:127], v[74:77], v[4:7]
	v_mfma_f32_16x16x32_bf16 v[48:51], v[124:127], v[78:81], v[48:51]
	v_mfma_f32_16x16x32_bf16 v[32:35], v[124:127], v[82:85], v[32:35]
	s_waitcnt lgkmcnt(0)
	s_barrier
	s_cmp_eq_u32 s42, 0x1500
	s_cbranch_scc1 .Lv3_nodma_G7
	s_mov_b32 m0, s35
	v_mfma_f32_16x16x32_bf16 v[64:67], v[144:147], v[128:131], v[64:67]
	global_load_lds_dwordx4 v164, s[52:53]
	s_add_u32 m0, s35, 0x1000
	v_mfma_f32_16x16x32_bf16 v[60:63], v[144:147], v[132:135], v[60:63]
	global_load_lds_dwordx4 v165, s[52:53]
	s_add_u32 m0, s35, 0x2000
	v_mfma_f32_16x16x32_bf16 v[56:59], v[144:147], v[136:139], v[56:59]
	global_load_lds_dwordx4 v166, s[52:53]
	s_add_u32 m0, s35, 0x3000
	v_mfma_f32_16x16x32_bf16 v[52:55], v[144:147], v[140:143], v[52:55]
	global_load_lds_dwordx4 v167, s[52:53]
	s_add_u32 m0, s35, 0x4000
	v_mfma_f32_16x16x32_bf16 v[44:47], v[148:151], v[128:131], v[44:47]
	global_load_lds_dwordx4 v164, s[54:55]
	s_add_u32 m0, s35, 0x5000
	v_mfma_f32_16x16x32_bf16 v[40:43], v[148:151], v[132:135], v[40:43]
	global_load_lds_dwordx4 v165, s[54:55]
	s_add_u32 m0, s35, 0x6000
	v_mfma_f32_16x16x32_bf16 v[36:39], v[148:151], v[136:139], v[36:39]
	global_load_lds_dwordx4 v166, s[54:55]
	s_add_u32 m0, s35, 0x7000
	v_mfma_f32_16x16x32_bf16 v[28:31], v[148:151], v[140:143], v[28:31]
	global_load_lds_dwordx4 v167, s[54:55]
	s_add_u32 s52, s52, 0x80
	s_addc_u32 s53, s53, 0
	s_add_u32 s54, s54, 0x80
	s_addc_u32 s55, s55, 0
	s_xor_b32 s35, s35, 0x8000
	s_branch .Lv3_join_G7
.Lv3_nodma_G7:
	v_mfma_f32_16x16x32_bf16 v[64:67], v[144:147], v[128:131], v[64:67]
	v_mfma_f32_16x16x32_bf16 v[60:63], v[144:147], v[132:135], v[60:63]
	v_mfma_f32_16x16x32_bf16 v[56:59], v[144:147], v[136:139], v[56:59]
	v_mfma_f32_16x16x32_bf16 v[52:55], v[144:147], v[140:143], v[52:55]
	v_mfma_f32_16x16x32_bf16 v[44:47], v[148:151], v[128:131], v[44:47]
	v_mfma_f32_16x16x32_bf16 v[40:43], v[148:151], v[132:135], v[40:43]
	v_mfma_f32_16x16x32_bf16 v[36:39], v[148:151], v[136:139], v[36:39]
	v_mfma_f32_16x16x32_bf16 v[28:31], v[148:151], v[140:143], v[28:31]
.Lv3_join_G7:
	s_add_u32 s42, s42, 0x80
	s_cmpk_eq_i32 s42, 0x1580
	v_mfma_f32_16x16x32_bf16 v[24:27], v[152:155], v[128:131], v[24:27]
	v_mfma_f32_16x16x32_bf16 v[20:23], v[152:155], v[132:135], v[20:23]
	v_mfma_f32_16x16x32_bf16 v[16:19], v[152:155], v[136:139], v[16:19]
	v_mfma_f32_16x16x32_bf16 v[12:15], v[152:155], v[140:143], v[12:15]
	v_mfma_f32_16x16x32_bf16 v[8:11], v[156:159], v[128:131], v[8:11]
	v_mfma_f32_16x16x32_bf16 v[4:7], v[156:159], v[132:135], v[4:7]
	v_mfma_f32_16x16x32_bf16 v[48:51], v[156:159], v[136:139], v[48:51]
	v_mfma_f32_16x16x32_bf16 v[32:35], v[156:159], v[140:143], v[32:35]
	s_cbranch_scc0 .LBB0_105
	s_waitcnt vmcnt(0)
	s_barrier
	s_mov_b32 s49, 0x8000
	v_lshl_add_u32 v69, v69, 1, s49
	v_add_u32_e32 v90, v69, v68
	ds_read_b128 v[70:73], v90 offset:16384
	v_add_u32_e32 v69, v69, v3
	ds_read_b128 v[74:77], v69
	ds_read_b128 v[78:81], v69 offset:2048
	ds_read_b128 v[82:85], v69 offset:4096
	ds_read_b128 v[86:89], v69 offset:6144
	v_lshl_add_u32 v1, v1, 1, s49
	v_add_u32_e32 v98, v1, v68
	ds_read_b128 v[94:97], v98 offset:20480
	s_waitcnt lgkmcnt(4)
	v_mfma_f32_16x16x32_bf16 v[64:67], v[70:73], v[74:77], v[64:67]
	v_add_u32_e32 v1, v1, v3
	s_add_i32 s44, s44, 1
	v_readlane_b32 s1, v254, 22
	s_waitcnt lgkmcnt(3)
	v_mfma_f32_16x16x32_bf16 v[60:63], v[70:73], v[78:81], v[60:63]
	s_mul_i32 s2, s44, s1
	v_readlane_b32 s1, v253, 34
	s_add_i32 s2, s2, s1
	s_waitcnt lgkmcnt(2)
	v_mfma_f32_16x16x32_bf16 v[56:59], v[70:73], v[82:85], v[56:59]
	s_cmpk_gt_u32 s2, 0x5f
	s_cselect_b64 s[36:37], -1, 0
	s_lshr_b32 s42, s2, 3
	s_waitcnt lgkmcnt(1)
	v_mfma_f32_16x16x32_bf16 v[52:55], v[70:73], v[86:89], v[52:55]
	ds_read_b128 v[70:73], v90 offset:18432
	v_readlane_b32 s1, v253, 62
	s_min_u32 s3, s2, 0x60
	s_waitcnt lgkmcnt(0)
	v_mfma_f32_16x16x32_bf16 v[44:47], v[70:73], v[74:77], v[44:47]
	s_add_i32 s42, s42, s1
	s_and_b32 s43, s3, 7
	s_cmpk_lt_u32 s2, 0x60
	v_mfma_f32_16x16x32_bf16 v[40:43], v[70:73], v[78:81], v[40:43]
	v_mfma_f32_16x16x32_bf16 v[36:39], v[70:73], v[82:85], v[36:39]
	v_mfma_f32_16x16x32_bf16 v[28:31], v[70:73], v[86:89], v[28:31]
	ds_read_b128 v[70:73], v90 offset:20480
	s_waitcnt lgkmcnt(0)
	v_mfma_f32_16x16x32_bf16 v[24:27], v[70:73], v[74:77], v[24:27]
	v_mfma_f32_16x16x32_bf16 v[20:23], v[70:73], v[78:81], v[20:23]
	v_mfma_f32_16x16x32_bf16 v[16:19], v[70:73], v[82:85], v[16:19]
	v_mfma_f32_16x16x32_bf16 v[12:15], v[70:73], v[86:89], v[12:15]
	ds_read_b128 v[70:73], v90 offset:22528
	ds_read_b128 v[90:93], v1 offset:6144
	s_waitcnt lgkmcnt(1)
	v_mfma_f32_16x16x32_bf16 v[8:11], v[70:73], v[74:77], v[8:11]
	v_mfma_f32_16x16x32_bf16 v[4:7], v[70:73], v[78:81], v[4:7]
	ds_read_b128 v[78:81], v1
	v_mfma_f32_16x16x32_bf16 v[74:77], v[70:73], v[82:85], v[48:51]
	ds_read_b128 v[82:85], v1 offset:2048
	s_nop 1
	ds_read_b128 v[48:51], v98 offset:16384
	v_mfma_f32_16x16x32_bf16 v[68:71], v[70:73], v[86:89], v[32:35]
	ds_read_b128 v[86:89], v1 offset:4096
	s_nop 1
	ds_read_b128 v[32:35], v98 offset:18432
	ds_read_b128 v[98:101], v98 offset:22528
	s_waitcnt lgkmcnt(3)
	v_mfma_f32_16x16x32_bf16 v[64:67], v[48:51], v[78:81], v[64:67]
	s_waitcnt vmcnt(0)
	s_waitcnt lgkmcnt(0)
	s_barrier
	v_mfma_f32_16x16x32_bf16 v[60:63], v[48:51], v[82:85], v[60:63]
	v_mfma_f32_16x16x32_bf16 v[56:59], v[48:51], v[86:89], v[56:59]
	v_mfma_f32_16x16x32_bf16 v[52:55], v[48:51], v[90:93], v[52:55]
	v_mfma_f32_16x16x32_bf16 v[48:51], v[32:35], v[78:81], v[44:47]
	v_mfma_f32_16x16x32_bf16 v[44:47], v[32:35], v[82:85], v[40:43]
	v_mfma_f32_16x16x32_bf16 v[40:43], v[32:35], v[86:89], v[36:39]
	v_mfma_f32_16x16x32_bf16 v[36:39], v[32:35], v[90:93], v[28:31]
	v_mfma_f32_16x16x32_bf16 v[32:35], v[94:97], v[78:81], v[24:27]
	v_mfma_f32_16x16x32_bf16 v[28:31], v[94:97], v[82:85], v[20:23]
	v_mfma_f32_16x16x32_bf16 v[24:27], v[94:97], v[86:89], v[16:19]
	v_mfma_f32_16x16x32_bf16 v[20:23], v[94:97], v[90:93], v[12:15]
	v_mfma_f32_16x16x32_bf16 v[16:19], v[98:101], v[78:81], v[8:11]
	v_mfma_f32_16x16x32_bf16 v[12:15], v[98:101], v[82:85], v[4:7]
	v_mfma_f32_16x16x32_bf16 v[8:11], v[98:101], v[86:89], v[74:77]
	v_mfma_f32_16x16x32_bf16 v[4:7], v[98:101], v[90:93], v[68:71]
	s_cbranch_scc0 .LBB0_99
	s_mul_i32 s30, s42, 0x58000
	s_lshl_b64 s[2:3], s[30:31], 1
	v_readlane_b32 s18, v252, 26
	v_readlane_b32 s19, v252, 27
	s_add_u32 s2, s18, s2
	s_addc_u32 s3, s19, s3
	s_mul_i32 s20, s43, 0xb0000
	v_readlane_b32 s1, v252, 28
	s_add_u32 s20, s1, s20
	v_readlane_b32 s1, v252, 29
	v_mov_b32_e32 v1, v168
	s_addc_u32 s21, s1, 0
	v_mov_b64_e32 v[68:69], s[2:3]
	v_ashrrev_i32_e32 v3, 3, v1
	v_xor_b32_e32 v70, v3, v1
	v_mov_b64_e32 v[72:73], s[20:21]
	v_mad_i64_i32 v[68:69], s[2:3], v3, s34, v[68:69]
	v_lshlrev_b32_e32 v70, 4, v70
	v_mad_i64_i32 v[72:73], s[2:3], v3, s34, v[72:73]
	v_lshlrev_b32_e32 v1, 4, v1
	v_and_b32_e32 v70, 0x70, v70
	v_mov_b32_e32 v71, v2
	v_readfirstlane_b32 s2, v1
	v_add_u32_e32 v3, 0x1000, v1
	v_lshl_add_u64 v[68:69], v[68:69], 0, v[70:71]
	s_mov_b32 m0, s2
	s_mov_b64 s[18:19], 0x2c000
	v_readfirstlane_b32 s2, v3
	v_add_u32_e32 v3, 0x2000, v1
	global_load_lds_dwordx4 v[68:69], off
	v_lshl_add_u64 v[74:75], v[68:69], 0, s[18:19]
	s_mov_b32 m0, s2
	s_mov_b64 s[20:21], 0x58000
	v_readfirstlane_b32 s2, v3
	v_add_u32_e32 v3, 0x3000, v1
	global_load_lds_dwordx4 v[74:75], off
	v_lshl_add_u64 v[74:75], v[68:69], 0, s[20:21]
	s_mov_b32 m0, s2
	s_mov_b64 s[34:35], 0x84000
	v_readfirstlane_b32 s2, v3
	v_add_u32_e32 v3, 0x4000, v1
	global_load_lds_dwordx4 v[74:75], off
	v_lshl_add_u64 v[68:69], v[68:69], 0, s[34:35]
	s_mov_b32 m0, s2
	v_readfirstlane_b32 s2, v3
	v_add_u32_e32 v3, 0x5000, v1
	global_load_lds_dwordx4 v[68:69], off
	v_lshl_add_u64 v[68:69], v[72:73], 0, v[70:71]
	s_mov_b32 m0, s2
	v_readfirstlane_b32 s2, v3
	v_add_u32_e32 v3, 0x6000, v1
	global_load_lds_dwordx4 v[68:69], off
	v_lshl_add_u64 v[70:71], v[68:69], 0, s[18:19]
	s_mov_b32 m0, s2
	v_readfirstlane_b32 s2, v3
	v_add_u32_e32 v1, 0x7000, v1
	global_load_lds_dwordx4 v[70:71], off
	v_lshl_add_u64 v[70:71], v[68:69], 0, s[20:21]
	s_mov_b32 m0, s2
	v_readfirstlane_b32 s2, v1
	global_load_lds_dwordx4 v[70:71], off
	v_lshl_add_u64 v[68:69], v[68:69], 0, s[34:35]
	s_mov_b32 m0, s2
	s_nop 0
	global_load_lds_dwordx4 v[68:69], off
	s_branch .LBB0_99

.LBB0_121:
	v_mov_b32_e32 v1, v168
	v_readlane_b32 s60, v254, 48
	v_readfirstlane_b32 s2, v1
	s_lshl_b32 s3, s2, 5
	s_lshl_b32 s2, s2, 6
	s_and_b32 s3, s3, 0xfffff000
	s_and_b32 s2, s2, 0x1000
	v_readlane_b32 s64, v254, 52
	v_lshrrev_b32_e32 v3, 4, v1
	v_and_b32_e32 v4, 7, v1
	v_lshlrev_b32_e32 v1, 6, v1
	v_readlane_b32 s65, v254, 53
	s_add_u32 s50, s64, s50
	v_bitop3_b32 v3, v3, v4, 3 bitop3:0x6c
	s_waitcnt vmcnt(0)
	v_and_b32_e32 v1, 0x3c0, v1
	s_addc_u32 s51, s65, s51
	v_lshlrev_b32_e32 v69, 3, v3
	v_or_b32_e32 v3, s3, v1
	v_or_b32_e32 v4, s2, v1
	s_add_u32 s52, s64, s52
	s_waitcnt lgkmcnt(0)
	v_mov_b32_e32 v32, 0
	v_xor_b32_e32 v1, 32, v69
	s_addc_u32 s53, s65, s53
	s_mov_b64 s[54:55], 0
	s_mov_b32 s45, 0
	v_lshlrev_b32_e32 v3, 1, v3
	v_lshlrev_b32_e32 v68, 1, v4
	v_mov_b32_e32 v33, v32
	v_mov_b32_e32 v34, v32
	v_mov_b32_e32 v35, v32
	v_mov_b32_e32 v48, v32
	v_mov_b32_e32 v49, v32
	v_mov_b32_e32 v50, v32
	v_mov_b32_e32 v51, v32
	v_mov_b32_e32 v4, v32
	v_mov_b32_e32 v5, v32
	v_mov_b32_e32 v6, v32
	v_mov_b32_e32 v7, v32
	v_mov_b32_e32 v8, v32
	v_mov_b32_e32 v9, v32
	v_mov_b32_e32 v10, v32
	v_mov_b32_e32 v11, v32
	v_mov_b32_e32 v12, v32
	v_mov_b32_e32 v13, v32
	v_mov_b32_e32 v14, v32
	v_mov_b32_e32 v15, v32
	v_mov_b32_e32 v16, v32
	v_mov_b32_e32 v17, v32
	v_mov_b32_e32 v18, v32
	v_mov_b32_e32 v19, v32
	v_mov_b32_e32 v20, v32
	v_mov_b32_e32 v21, v32
	v_mov_b32_e32 v22, v32
	v_mov_b32_e32 v23, v32
	v_mov_b32_e32 v24, v32
	v_mov_b32_e32 v25, v32
	v_mov_b32_e32 v26, v32
	v_mov_b32_e32 v27, v32
	v_mov_b32_e32 v28, v32
	v_mov_b32_e32 v29, v32
	v_mov_b32_e32 v30, v32
	v_mov_b32_e32 v31, v32
	v_mov_b32_e32 v36, v32
	v_mov_b32_e32 v37, v32
	v_mov_b32_e32 v38, v32
	v_mov_b32_e32 v39, v32
	v_mov_b32_e32 v40, v32
	v_mov_b32_e32 v41, v32
	v_mov_b32_e32 v42, v32
	v_mov_b32_e32 v43, v32
	v_mov_b32_e32 v44, v32
	v_mov_b32_e32 v45, v32
	v_mov_b32_e32 v46, v32
	v_mov_b32_e32 v47, v32
	v_mov_b32_e32 v52, v32
	v_mov_b32_e32 v53, v32
	v_mov_b32_e32 v54, v32
	v_mov_b32_e32 v55, v32
	v_mov_b32_e32 v56, v32
	v_mov_b32_e32 v57, v32
	v_mov_b32_e32 v58, v32
	v_mov_b32_e32 v59, v32
	v_mov_b32_e32 v60, v32
	v_mov_b32_e32 v61, v32
	v_mov_b32_e32 v62, v32
	v_mov_b32_e32 v63, v32
	v_mov_b32_e32 v64, v32
	v_mov_b32_e32 v65, v32
	v_mov_b32_e32 v66, v32
	v_mov_b32_e32 v67, v32
	s_waitcnt vmcnt(0) lgkmcnt(0)
	s_barrier
	v_readlane_b32 s61, v254, 49
	v_readlane_b32 s62, v254, 50
	v_readlane_b32 s63, v254, 51
	v_readlane_b32 s66, v254, 54
	v_readlane_b32 s67, v254, 55
	v_lshlrev_b32_e32 v86, 1, v69
	v_add_u32_e32 v160, v3, v86
	v_add_u32_e32 v162, v68, v86
	v_lshlrev_b32_e32 v86, 1, v1
	v_add_u32_e32 v161, v3, v86
	v_add_u32_e32 v163, v68, v86
	v_lshrrev_b32_e32 v87, 3, v168
	v_xor_b32_e32 v86, v87, v168
	v_and_b32_e32 v86, 7, v86
	v_lshlrev_b32_e32 v86, 4, v86
	s_movk_i32 s60, 0x800
	v_mad_u32_u24 v164, v87, s60, v86
	v_add_u32_e32 v165, 0x10000, v164
	v_add_u32_e32 v166, 0x20000, v164
	v_add_u32_e32 v167, 0x30000, v164
	s_add_u32 s58, s50, s68
	s_addc_u32 s59, s51, s69
	s_add_u32 s34, s52, 0xa130080
	s_addc_u32 s35, s53, 0
	v_readfirstlane_b32 s60, v168
	s_lshl_b32 s60, s60, 4
	s_or_b32 s60, s60, 0x8000
	s_mov_b32 m0, s60
	s_nop 0
	global_load_lds_dwordx4 v164, s[58:59]
	s_add_u32 m0, s60, 0x1000
	s_nop 0
	global_load_lds_dwordx4 v165, s[58:59]
	s_add_u32 m0, s60, 0x2000
	s_nop 0
	global_load_lds_dwordx4 v166, s[58:59]
	s_add_u32 m0, s60, 0x3000
	s_nop 0
	global_load_lds_dwordx4 v167, s[58:59]
	s_add_u32 m0, s60, 0x4000
	s_nop 0
	global_load_lds_dwordx4 v164, s[34:35]
	s_add_u32 m0, s60, 0x5000
	s_nop 0
	global_load_lds_dwordx4 v165, s[34:35]
	s_add_u32 m0, s60, 0x6000
	s_nop 0
	global_load_lds_dwordx4 v166, s[34:35]
	s_add_u32 m0, s60, 0x7000
	s_nop 0
	global_load_lds_dwordx4 v167, s[34:35]
	s_add_u32 s58, s58, 0x80
	s_addc_u32 s59, s59, 0
	s_add_u32 s34, s34, 0x80
	s_addc_u32 s35, s35, 0
	s_xor_b32 s60, s60, 0x8000
.LBB0_122:
	s_waitcnt vmcnt(8)
	s_barrier
	ds_read_b128 v[70:73], v160
	ds_read_b128 v[74:77], v160 offset:2048
	ds_read_b128 v[78:81], v160 offset:4096
	ds_read_b128 v[82:85], v160 offset:6144
	ds_read_b128 v[112:115], v162 offset:16384
	ds_read_b128 v[116:119], v162 offset:18432
	ds_read_b128 v[120:123], v162 offset:20480
	ds_read_b128 v[124:127], v162 offset:22528
	ds_read_b128 v[128:131], v161
	ds_read_b128 v[132:135], v161 offset:2048
	ds_read_b128 v[136:139], v161 offset:4096
	ds_read_b128 v[140:143], v161 offset:6144
	ds_read_b128 v[144:147], v163 offset:16384
	ds_read_b128 v[148:151], v163 offset:18432
	ds_read_b128 v[152:155], v163 offset:20480
	s_waitcnt lgkmcnt(10)
	v_mfma_f32_16x16x32_bf16 v[64:67], v[112:115], v[70:73], v[64:67]
	v_mfma_f32_16x16x32_bf16 v[60:63], v[112:115], v[74:77], v[60:63]
	v_mfma_f32_16x16x32_bf16 v[56:59], v[112:115], v[78:81], v[56:59]
	v_mfma_f32_16x16x32_bf16 v[52:55], v[112:115], v[82:85], v[52:55]
	ds_read_b128 v[156:159], v163 offset:22528
	s_waitcnt lgkmcnt(10)
	v_mfma_f32_16x16x32_bf16 v[44:47], v[116:119], v[70:73], v[44:47]
	v_mfma_f32_16x16x32_bf16 v[40:43], v[116:119], v[74:77], v[40:43]
	v_mfma_f32_16x16x32_bf16 v[36:39], v[116:119], v[78:81], v[36:39]
	v_mfma_f32_16x16x32_bf16 v[28:31], v[116:119], v[82:85], v[28:31]
	v_xor_b32_e32 v160, 0x8000, v160
	v_xor_b32_e32 v162, 0x8000, v162
	s_waitcnt lgkmcnt(9)
	v_mfma_f32_16x16x32_bf16 v[24:27], v[120:123], v[70:73], v[24:27]
	v_mfma_f32_16x16x32_bf16 v[20:23], v[120:123], v[74:77], v[20:23]
	v_mfma_f32_16x16x32_bf16 v[16:19], v[120:123], v[78:81], v[16:19]
	v_mfma_f32_16x16x32_bf16 v[12:15], v[120:123], v[82:85], v[12:15]
	v_xor_b32_e32 v161, 0x8000, v161
	v_xor_b32_e32 v163, 0x8000, v163
	s_waitcnt lgkmcnt(8)
	v_mfma_f32_16x16x32_bf16 v[8:11], v[124:127], v[70:73], v[8:11]
	v_mfma_f32_16x16x32_bf16 v[4:7], v[124:127], v[74:77], v[4:7]
	v_mfma_f32_16x16x32_bf16 v[48:51], v[124:127], v[78:81], v[48:51]
	v_mfma_f32_16x16x32_bf16 v[32:35], v[124:127], v[82:85], v[32:35]
	s_waitcnt lgkmcnt(0)
	s_barrier
	s_cmp_eq_u32 s54, 0x700
	s_cbranch_scc1 .Lv3_nodma_G6
	s_mov_b32 m0, s60
	v_mfma_f32_16x16x32_bf16 v[64:67], v[144:147], v[128:131], v[64:67]
	global_load_lds_dwordx4 v164, s[58:59]
	s_add_u32 m0, s60, 0x1000
	v_mfma_f32_16x16x32_bf16 v[60:63], v[144:147], v[132:135], v[60:63]
	global_load_lds_dwordx4 v165, s[58:59]
	s_add_u32 m0, s60, 0x2000
	v_mfma_f32_16x16x32_bf16 v[56:59], v[144:147], v[136:139], v[56:59]
	global_load_lds_dwordx4 v166, s[58:59]
	s_add_u32 m0, s60, 0x3000
	v_mfma_f32_16x16x32_bf16 v[52:55], v[144:147], v[140:143], v[52:55]
	global_load_lds_dwordx4 v167, s[58:59]
	s_add_u32 m0, s60, 0x4000
	v_mfma_f32_16x16x32_bf16 v[44:47], v[148:151], v[128:131], v[44:47]
	global_load_lds_dwordx4 v164, s[34:35]
	s_add_u32 m0, s60, 0x5000
	v_mfma_f32_16x16x32_bf16 v[40:43], v[148:151], v[132:135], v[40:43]
	global_load_lds_dwordx4 v165, s[34:35]
	s_add_u32 m0, s60, 0x6000
	v_mfma_f32_16x16x32_bf16 v[36:39], v[148:151], v[136:139], v[36:39]
	global_load_lds_dwordx4 v166, s[34:35]
	s_add_u32 m0, s60, 0x7000
	v_mfma_f32_16x16x32_bf16 v[28:31], v[148:151], v[140:143], v[28:31]
	global_load_lds_dwordx4 v167, s[34:35]
	s_add_u32 s58, s58, 0x80
	s_addc_u32 s59, s59, 0
	s_add_u32 s34, s34, 0x80
	s_addc_u32 s35, s35, 0
	s_xor_b32 s60, s60, 0x8000
	s_branch .Lv3_join_G6

.Lv3_join_G6:
	s_add_u32 s54, s54, 0x80
	s_cmpk_eq_i32 s54, 0x780
	v_mfma_f32_16x16x32_bf16 v[24:27], v[152:155], v[128:131], v[24:27]
	v_mfma_f32_16x16x32_bf16 v[20:23], v[152:155], v[132:135], v[20:23]
	v_mfma_f32_16x16x32_bf16 v[16:19], v[152:155], v[136:139], v[16:19]
	v_mfma_f32_16x16x32_bf16 v[12:15], v[152:155], v[140:143], v[12:15]
	v_mfma_f32_16x16x32_bf16 v[8:11], v[156:159], v[128:131], v[8:11]
	v_mfma_f32_16x16x32_bf16 v[4:7], v[156:159], v[132:135], v[4:7]
	v_mfma_f32_16x16x32_bf16 v[48:51], v[156:159], v[136:139], v[48:51]
	v_mfma_f32_16x16x32_bf16 v[32:35], v[156:159], v[140:143], v[32:35]
	s_cbranch_scc0 .LBB0_122
	s_waitcnt vmcnt(0)
	s_barrier
	s_mov_b32 s37, 0x8000
	v_lshl_add_u32 v69, v69, 1, s37
	v_add_u32_e32 v102, v69, v68
	ds_read_b128 v[70:73], v102 offset:16384
	v_add_u32_e32 v69, v69, v3
	ds_read_b128 v[74:77], v69
	ds_read_b128 v[78:81], v69 offset:2048
	v_lshl_add_u32 v1, v1, 1, s37
	v_add_u32_e32 v68, v1, v68
	v_add_u32_e32 v1, v1, v3
	s_and_b64 vcc, exec, s[48:49]
	s_waitcnt lgkmcnt(0)
	v_mfma_f32_16x16x32_bf16 v[82:85], v[70:73], v[78:81], v[60:63]
	ds_read_b128 v[86:89], v69 offset:6144
	ds_read_b128 v[106:109], v1 offset:6144
	s_nop 0
	ds_read_b128 v[60:63], v69 offset:4096
	v_mfma_f32_16x16x32_bf16 v[64:67], v[70:73], v[74:77], v[64:67]
	s_waitcnt lgkmcnt(0)
	v_mfma_f32_16x16x32_bf16 v[56:59], v[70:73], v[60:63], v[56:59]
	v_mfma_f32_16x16x32_bf16 v[70:73], v[70:73], v[86:89], v[52:55]
	s_nop 2
	ds_read_b128 v[52:55], v102 offset:18432
	s_waitcnt lgkmcnt(0)
	v_mfma_f32_16x16x32_bf16 v[94:97], v[52:55], v[60:63], v[36:39]
	s_nop 2
	ds_read_b128 v[36:39], v102 offset:20480
	s_waitcnt lgkmcnt(0)
	v_mfma_f32_16x16x32_bf16 v[98:101], v[36:39], v[86:89], v[12:15]
	s_nop 2
	ds_read_b128 v[12:15], v102 offset:22528
	ds_read_b128 v[102:105], v1 offset:2048
	v_mfma_f32_16x16x32_bf16 v[90:93], v[52:55], v[74:77], v[44:47]
	v_mfma_f32_16x16x32_bf16 v[24:27], v[36:39], v[74:77], v[24:27]
	s_waitcnt lgkmcnt(1)
	v_mfma_f32_16x16x32_bf16 v[8:11], v[12:15], v[74:77], v[8:11]
	v_mfma_f32_16x16x32_bf16 v[74:77], v[12:15], v[78:81], v[4:7]
	s_nop 2
	ds_read_b128 v[4:7], v68 offset:16384
	v_mfma_f32_16x16x32_bf16 v[28:31], v[52:55], v[86:89], v[28:31]
	v_mfma_f32_16x16x32_bf16 v[86:89], v[12:15], v[86:89], v[32:35]
	s_nop 2
	ds_read_b128 v[32:35], v1
	v_mfma_f32_16x16x32_bf16 v[40:43], v[52:55], v[78:81], v[40:43]
	s_waitcnt lgkmcnt(1)
	v_mfma_f32_16x16x32_bf16 v[52:55], v[4:7], v[102:105], v[82:85]
	s_nop 2
	ds_read_b128 v[82:85], v1 offset:4096
	v_mfma_f32_16x16x32_bf16 v[20:23], v[36:39], v[78:81], v[20:23]
	v_mfma_f32_16x16x32_bf16 v[16:19], v[36:39], v[60:63], v[16:19]
	v_mfma_f32_16x16x32_bf16 v[78:81], v[12:15], v[60:63], v[48:51]
	s_waitcnt lgkmcnt(1)
	v_mfma_f32_16x16x32_bf16 v[60:63], v[4:7], v[32:35], v[64:67]
	s_waitcnt lgkmcnt(0)
	v_mfma_f32_16x16x32_bf16 v[44:47], v[4:7], v[82:85], v[56:59]
	v_mfma_f32_16x16x32_bf16 v[36:39], v[4:7], v[106:109], v[70:73]
	ds_read_b128 v[4:7], v68 offset:18432
	s_waitcnt lgkmcnt(0)
	v_mfma_f32_16x16x32_bf16 v[64:67], v[4:7], v[32:35], v[90:93]
	v_mfma_f32_16x16x32_bf16 v[56:59], v[4:7], v[102:105], v[40:43]
	v_mfma_f32_16x16x32_bf16 v[48:51], v[4:7], v[82:85], v[94:97]
	v_mfma_f32_16x16x32_bf16 v[40:43], v[4:7], v[106:109], v[28:31]
	ds_read_b128 v[4:7], v68 offset:20480
	ds_read_b128 v[68:71], v68 offset:22528
	s_waitcnt vmcnt(0)
	s_waitcnt lgkmcnt(1)
	v_mfma_f32_16x16x32_bf16 v[28:31], v[4:7], v[32:35], v[24:27]
	s_waitcnt lgkmcnt(0)
	s_barrier
	v_mfma_f32_16x16x32_bf16 v[20:23], v[4:7], v[102:105], v[20:23]
	v_mfma_f32_16x16x32_bf16 v[12:15], v[4:7], v[82:85], v[16:19]
	v_mfma_f32_16x16x32_bf16 v[4:7], v[4:7], v[106:109], v[98:101]
	v_mfma_f32_16x16x32_bf16 v[32:35], v[68:71], v[32:35], v[8:11]
	v_mfma_f32_16x16x32_bf16 v[24:27], v[68:71], v[102:105], v[74:77]
	v_mfma_f32_16x16x32_bf16 v[16:19], v[68:71], v[82:85], v[78:81]
	v_mfma_f32_16x16x32_bf16 v[8:11], v[68:71], v[106:109], v[86:89]
	s_cbranch_vccz .LBB0_125
	s_ashr_i32 s45, s44, 31
	v_mov_b32_e32 v1, v168
	s_lshl_b64 s[2:3], s[44:45], 18
	v_readlane_b32 s18, v252, 32
	v_readlane_b32 s19, v252, 33
	v_ashrrev_i32_e32 v68, 3, v1
	s_add_u32 s2, s18, s2
	v_xor_b32_e32 v3, v68, v1
	v_ashrrev_i32_e32 v69, 31, v68
	s_addc_u32 s3, s19, s3
	v_lshlrev_b64 v[68:69], 11, v[68:69]
	v_lshlrev_b32_e32 v3, 4, v3
	v_lshlrev_b32_e32 v1, 4, v1
	s_ashr_i32 s37, s36, 31
	v_lshl_add_u64 v[70:71], s[2:3], 0, v[68:69]
	v_and_b32_e32 v72, 0x70, v3
	v_mov_b32_e32 v73, v2
	v_readfirstlane_b32 s2, v1
	v_add_u32_e32 v3, 0x1000, v1
	s_lshl_b64 s[20:21], s[36:37], 18
	v_readlane_b32 s1, v252, 34
	v_lshl_add_u64 v[70:71], v[70:71], 0, v[72:73]
	s_mov_b32 m0, s2
	v_readfirstlane_b32 s2, v3
	v_add_u32_e32 v3, 0x2000, v1
	s_add_u32 s20, s1, s20
	v_readlane_b32 s1, v252, 35
	global_load_lds_dwordx4 v[70:71], off
	v_lshl_add_u64 v[74:75], v[70:71], 0, s[24:25]
	s_mov_b32 m0, s2
	v_readfirstlane_b32 s2, v3
	v_add_u32_e32 v3, 0x3000, v1
	s_addc_u32 s21, s1, s21
	global_load_lds_dwordx4 v[74:75], off
	v_lshl_add_u64 v[74:75], v[70:71], 0, s[26:27]
	s_mov_b32 m0, s2
	v_readfirstlane_b32 s2, v3
	v_add_u32_e32 v3, 0x4000, v1
	v_lshl_add_u64 v[68:69], s[20:21], 0, v[68:69]
	global_load_lds_dwordx4 v[74:75], off
	v_lshl_add_u64 v[70:71], v[70:71], 0, s[28:29]
	s_mov_b32 m0, s2
	v_readfirstlane_b32 s2, v3
	v_add_u32_e32 v3, 0x5000, v1
	global_load_lds_dwordx4 v[70:71], off
	v_lshl_add_u64 v[68:69], v[68:69], 0, v[72:73]
	s_mov_b32 m0, s2
	v_readfirstlane_b32 s2, v3
	v_add_u32_e32 v3, 0x6000, v1
	global_load_lds_dwordx4 v[68:69], off
	v_lshl_add_u64 v[70:71], v[68:69], 0, s[24:25]
	s_mov_b32 m0, s2
	v_readfirstlane_b32 s2, v3
	v_add_u32_e32 v1, 0x7000, v1
	global_load_lds_dwordx4 v[70:71], off
	v_lshl_add_u64 v[70:71], v[68:69], 0, s[26:27]
	s_mov_b32 m0, s2
	v_readfirstlane_b32 s2, v1
	global_load_lds_dwordx4 v[70:71], off
	v_lshl_add_u64 v[68:69], v[68:69], 0, s[28:29]
	s_mov_b32 m0, s2
	s_nop 0
	global_load_lds_dwordx4 v[68:69], off

.LBB0_148:
	v_mov_b32_e32 v1, v168
	v_readlane_b32 s52, v254, 48
	v_readfirstlane_b32 s2, v1
	v_lshrrev_b32_e32 v3, 4, v1
	v_and_b32_e32 v4, 7, v1
	s_lshl_b32 s3, s2, 5
	v_lshlrev_b32_e32 v1, 6, v1
	s_lshl_b32 s2, s2, 6
	v_bitop3_b32 v3, v3, v4, 3 bitop3:0x6c
	s_and_b32 s3, s3, 0xfffff000
	v_and_b32_e32 v1, 0x3c0, v1
	s_and_b32 s2, s2, 0x1000
	v_lshlrev_b32_e32 v69, 3, v3
	v_or_b32_e32 v3, s3, v1
	v_or_b32_e32 v4, s2, v1
	s_lshl_b64 s[2:3], s[38:39], 11
	v_readlane_b32 s56, v254, 52
	v_readlane_b32 s57, v254, 53
	s_add_u32 s40, s56, s2
	s_waitcnt vmcnt(0)
	s_addc_u32 s41, s57, s3
	s_lshl_b64 s[2:3], s[30:31], 1
	s_add_u32 s42, s56, s2
	s_waitcnt lgkmcnt(0)
	v_mov_b32_e32 v32, 0
	v_xor_b32_e32 v1, 32, v69
	s_addc_u32 s43, s57, s3
	s_mov_b64 s[44:45], 0
	s_mov_b32 s51, 0
	v_lshlrev_b32_e32 v3, 1, v3
	v_lshlrev_b32_e32 v68, 1, v4
	v_mov_b32_e32 v33, v32
	v_mov_b32_e32 v34, v32
	v_mov_b32_e32 v35, v32
	v_mov_b32_e32 v48, v32
	v_mov_b32_e32 v49, v32
	v_mov_b32_e32 v50, v32
	v_mov_b32_e32 v51, v32
	v_mov_b32_e32 v4, v32
	v_mov_b32_e32 v5, v32
	v_mov_b32_e32 v6, v32
	v_mov_b32_e32 v7, v32
	v_mov_b32_e32 v8, v32
	v_mov_b32_e32 v9, v32
	v_mov_b32_e32 v10, v32
	v_mov_b32_e32 v11, v32
	v_mov_b32_e32 v12, v32
	v_mov_b32_e32 v13, v32
	v_mov_b32_e32 v14, v32
	v_mov_b32_e32 v15, v32
	v_mov_b32_e32 v16, v32
	v_mov_b32_e32 v17, v32
	v_mov_b32_e32 v18, v32
	v_mov_b32_e32 v19, v32
	v_mov_b32_e32 v20, v32
	v_mov_b32_e32 v21, v32
	v_mov_b32_e32 v22, v32
	v_mov_b32_e32 v23, v32
	v_mov_b32_e32 v24, v32
	v_mov_b32_e32 v25, v32
	v_mov_b32_e32 v26, v32
	v_mov_b32_e32 v27, v32
	v_mov_b32_e32 v28, v32
	v_mov_b32_e32 v29, v32
	v_mov_b32_e32 v30, v32
	v_mov_b32_e32 v31, v32
	v_mov_b32_e32 v36, v32
	v_mov_b32_e32 v37, v32
	v_mov_b32_e32 v38, v32
	v_mov_b32_e32 v39, v32
	v_mov_b32_e32 v40, v32
	v_mov_b32_e32 v41, v32
	v_mov_b32_e32 v42, v32
	v_mov_b32_e32 v43, v32
	v_mov_b32_e32 v44, v32
	v_mov_b32_e32 v45, v32
	v_mov_b32_e32 v46, v32
	v_mov_b32_e32 v47, v32
	v_mov_b32_e32 v52, v32
	v_mov_b32_e32 v53, v32
	v_mov_b32_e32 v54, v32
	v_mov_b32_e32 v55, v32
	v_mov_b32_e32 v56, v32
	v_mov_b32_e32 v57, v32
	v_mov_b32_e32 v58, v32
	v_mov_b32_e32 v59, v32
	v_mov_b32_e32 v60, v32
	v_mov_b32_e32 v61, v32
	v_mov_b32_e32 v62, v32
	v_mov_b32_e32 v63, v32
	v_mov_b32_e32 v64, v32
	v_mov_b32_e32 v65, v32
	v_mov_b32_e32 v66, v32
	v_mov_b32_e32 v67, v32
	s_mov_b64 s[18:19], 0x1390080
	s_waitcnt vmcnt(0) lgkmcnt(0)
	s_barrier
	v_readlane_b32 s53, v254, 49
	v_readlane_b32 s54, v254, 50
	v_readlane_b32 s55, v254, 51
	v_readlane_b32 s58, v254, 54
	v_readlane_b32 s59, v254, 55
	v_lshlrev_b32_e32 v86, 1, v69
	v_add_u32_e32 v160, v3, v86
	v_add_u32_e32 v162, v68, v86
	v_lshlrev_b32_e32 v86, 1, v1
	v_add_u32_e32 v161, v3, v86
	v_add_u32_e32 v163, v68, v86
	v_lshrrev_b32_e32 v87, 3, v168
	v_xor_b32_e32 v86, v87, v168
	v_and_b32_e32 v86, 7, v86
	v_lshlrev_b32_e32 v86, 4, v86
	s_movk_i32 s35, 0x800
	v_mad_u32_u24 v164, v87, s35, v86
	v_add_u32_e32 v165, 0x10000, v164
	v_add_u32_e32 v166, 0x20000, v164
	v_add_u32_e32 v167, 0x30000, v164
	s_add_u32 s52, s40, 0x1390080
	s_addc_u32 s53, s41, 0
	s_add_u32 s54, s42, 0x1190080
	s_addc_u32 s55, s43, 0
	v_readfirstlane_b32 s35, v168
	s_lshl_b32 s35, s35, 4
	s_or_b32 s35, s35, 0x8000
	s_mov_b32 m0, s35
	s_nop 0
	global_load_lds_dwordx4 v164, s[52:53]
	s_add_u32 m0, s35, 0x1000
	s_nop 0
	global_load_lds_dwordx4 v165, s[52:53]
	s_add_u32 m0, s35, 0x2000
	s_nop 0
	global_load_lds_dwordx4 v166, s[52:53]
	s_add_u32 m0, s35, 0x3000
	s_nop 0
	global_load_lds_dwordx4 v167, s[52:53]
	s_add_u32 m0, s35, 0x4000
	s_nop 0
	global_load_lds_dwordx4 v164, s[54:55]
	s_add_u32 m0, s35, 0x5000
	s_nop 0
	global_load_lds_dwordx4 v165, s[54:55]
	s_add_u32 m0, s35, 0x6000
	s_nop 0
	global_load_lds_dwordx4 v166, s[54:55]
	s_add_u32 m0, s35, 0x7000
	s_nop 0
	global_load_lds_dwordx4 v167, s[54:55]
	s_add_u32 s52, s52, 0x80
	s_addc_u32 s53, s53, 0
	s_add_u32 s54, s54, 0x80
	s_addc_u32 s55, s55, 0
	s_xor_b32 s35, s35, 0x8000
.LBB0_149:
	s_waitcnt vmcnt(8)
	s_barrier
	ds_read_b128 v[70:73], v160
	ds_read_b128 v[74:77], v160 offset:2048
	ds_read_b128 v[78:81], v160 offset:4096
	ds_read_b128 v[82:85], v160 offset:6144
	ds_read_b128 v[112:115], v162 offset:16384
	ds_read_b128 v[116:119], v162 offset:18432
	ds_read_b128 v[120:123], v162 offset:20480
	ds_read_b128 v[124:127], v162 offset:22528
	ds_read_b128 v[128:131], v161
	ds_read_b128 v[132:135], v161 offset:2048
	ds_read_b128 v[136:139], v161 offset:4096
	ds_read_b128 v[140:143], v161 offset:6144
	ds_read_b128 v[144:147], v163 offset:16384
	ds_read_b128 v[148:151], v163 offset:18432
	ds_read_b128 v[152:155], v163 offset:20480
	s_waitcnt lgkmcnt(10)
	v_mfma_f32_16x16x32_bf16 v[64:67], v[112:115], v[70:73], v[64:67]
	v_mfma_f32_16x16x32_bf16 v[60:63], v[112:115], v[74:77], v[60:63]
	v_mfma_f32_16x16x32_bf16 v[56:59], v[112:115], v[78:81], v[56:59]
	v_mfma_f32_16x16x32_bf16 v[52:55], v[112:115], v[82:85], v[52:55]
	ds_read_b128 v[156:159], v163 offset:22528
	s_waitcnt lgkmcnt(10)
	v_mfma_f32_16x16x32_bf16 v[44:47], v[116:119], v[70:73], v[44:47]
	v_mfma_f32_16x16x32_bf16 v[40:43], v[116:119], v[74:77], v[40:43]
	v_mfma_f32_16x16x32_bf16 v[36:39], v[116:119], v[78:81], v[36:39]
	v_mfma_f32_16x16x32_bf16 v[28:31], v[116:119], v[82:85], v[28:31]
	v_xor_b32_e32 v160, 0x8000, v160
	v_xor_b32_e32 v162, 0x8000, v162
	s_waitcnt lgkmcnt(9)
	v_mfma_f32_16x16x32_bf16 v[24:27], v[120:123], v[70:73], v[24:27]
	v_mfma_f32_16x16x32_bf16 v[20:23], v[120:123], v[74:77], v[20:23]
	v_mfma_f32_16x16x32_bf16 v[16:19], v[120:123], v[78:81], v[16:19]
	v_mfma_f32_16x16x32_bf16 v[12:15], v[120:123], v[82:85], v[12:15]
	v_xor_b32_e32 v161, 0x8000, v161
	v_xor_b32_e32 v163, 0x8000, v163
	s_waitcnt lgkmcnt(8)
	v_mfma_f32_16x16x32_bf16 v[8:11], v[124:127], v[70:73], v[8:11]
	v_mfma_f32_16x16x32_bf16 v[4:7], v[124:127], v[74:77], v[4:7]
	v_mfma_f32_16x16x32_bf16 v[48:51], v[124:127], v[78:81], v[48:51]
	v_mfma_f32_16x16x32_bf16 v[32:35], v[124:127], v[82:85], v[32:35]
	s_waitcnt lgkmcnt(0)
	s_barrier
	s_cmp_eq_u32 s44, 0x700
	s_cbranch_scc1 .Lv3_nodma_G5
	s_mov_b32 m0, s35
	v_mfma_f32_16x16x32_bf16 v[64:67], v[144:147], v[128:131], v[64:67]
	global_load_lds_dwordx4 v164, s[52:53]
	s_add_u32 m0, s35, 0x1000
	v_mfma_f32_16x16x32_bf16 v[60:63], v[144:147], v[132:135], v[60:63]
	global_load_lds_dwordx4 v165, s[52:53]
	s_add_u32 m0, s35, 0x2000
	v_mfma_f32_16x16x32_bf16 v[56:59], v[144:147], v[136:139], v[56:59]
	global_load_lds_dwordx4 v166, s[52:53]
	s_add_u32 m0, s35, 0x3000
	v_mfma_f32_16x16x32_bf16 v[52:55], v[144:147], v[140:143], v[52:55]
	global_load_lds_dwordx4 v167, s[52:53]
	s_add_u32 m0, s35, 0x4000
	v_mfma_f32_16x16x32_bf16 v[44:47], v[148:151], v[128:131], v[44:47]
	global_load_lds_dwordx4 v164, s[54:55]
	s_add_u32 m0, s35, 0x5000
	v_mfma_f32_16x16x32_bf16 v[40:43], v[148:151], v[132:135], v[40:43]
	global_load_lds_dwordx4 v165, s[54:55]
	s_add_u32 m0, s35, 0x6000
	v_mfma_f32_16x16x32_bf16 v[36:39], v[148:151], v[136:139], v[36:39]
	global_load_lds_dwordx4 v166, s[54:55]
	s_add_u32 m0, s35, 0x7000
	v_mfma_f32_16x16x32_bf16 v[28:31], v[148:151], v[140:143], v[28:31]
	global_load_lds_dwordx4 v167, s[54:55]
	s_add_u32 s52, s52, 0x80
	s_addc_u32 s53, s53, 0
	s_add_u32 s54, s54, 0x80
	s_addc_u32 s55, s55, 0
	s_xor_b32 s35, s35, 0x8000
	s_branch .Lv3_join_G5

.Lv3_join_G5:
	s_add_u32 s44, s44, 0x80
	s_cmpk_eq_i32 s44, 0x780
	v_mfma_f32_16x16x32_bf16 v[24:27], v[152:155], v[128:131], v[24:27]
	v_mfma_f32_16x16x32_bf16 v[20:23], v[152:155], v[132:135], v[20:23]
	v_mfma_f32_16x16x32_bf16 v[16:19], v[152:155], v[136:139], v[16:19]
	v_mfma_f32_16x16x32_bf16 v[12:15], v[152:155], v[140:143], v[12:15]
	v_mfma_f32_16x16x32_bf16 v[8:11], v[156:159], v[128:131], v[8:11]
	v_mfma_f32_16x16x32_bf16 v[4:7], v[156:159], v[132:135], v[4:7]
	v_mfma_f32_16x16x32_bf16 v[48:51], v[156:159], v[136:139], v[48:51]
	v_mfma_f32_16x16x32_bf16 v[32:35], v[156:159], v[140:143], v[32:35]
	s_cbranch_scc0 .LBB0_149
	s_waitcnt vmcnt(0)
	s_barrier
	s_mov_b32 s39, 0x8000
	v_lshl_add_u32 v69, v69, 1, s39
	v_add_u32_e32 v90, v69, v68
	ds_read_b128 v[70:73], v90 offset:16384
	v_add_u32_e32 v69, v69, v3
	ds_read_b128 v[74:77], v69
	ds_read_b128 v[78:81], v69 offset:2048
	ds_read_b128 v[82:85], v69 offset:4096
	ds_read_b128 v[86:89], v69 offset:6144
	v_lshl_add_u32 v1, v1, 1, s39
	v_add_u32_e32 v98, v1, v68
	ds_read_b128 v[94:97], v98 offset:20480
	s_waitcnt lgkmcnt(4)
	v_mfma_f32_16x16x32_bf16 v[64:67], v[70:73], v[74:77], v[64:67]
	v_add_u32_e32 v1, v1, v3
	s_add_i32 s46, s46, 1
	v_readlane_b32 s1, v254, 22
	s_waitcnt lgkmcnt(3)
	v_mfma_f32_16x16x32_bf16 v[60:63], v[70:73], v[78:81], v[60:63]
	s_mul_i32 s2, s46, s1
	v_readlane_b32 s1, v253, 34
	s_add_i32 s2, s2, s1
	s_waitcnt lgkmcnt(2)
	v_mfma_f32_16x16x32_bf16 v[56:59], v[70:73], v[82:85], v[56:59]
	s_cmpk_gt_u32 s2, 0x5f
	s_cselect_b64 s[40:41], -1, 0
	s_lshr_b32 s44, s2, 3
	s_waitcnt lgkmcnt(1)
	v_mfma_f32_16x16x32_bf16 v[52:55], v[70:73], v[86:89], v[52:55]
	ds_read_b128 v[70:73], v90 offset:18432
	v_readlane_b32 s1, v253, 62
	s_min_u32 s3, s2, 0x60
	s_waitcnt lgkmcnt(0)
	v_mfma_f32_16x16x32_bf16 v[44:47], v[70:73], v[74:77], v[44:47]
	s_add_i32 s44, s44, s1
	s_and_b32 s45, s3, 7
	s_cmpk_lt_u32 s2, 0x60
	v_mfma_f32_16x16x32_bf16 v[40:43], v[70:73], v[78:81], v[40:43]
	v_mfma_f32_16x16x32_bf16 v[36:39], v[70:73], v[82:85], v[36:39]
	v_mfma_f32_16x16x32_bf16 v[28:31], v[70:73], v[86:89], v[28:31]
	ds_read_b128 v[70:73], v90 offset:20480
	s_waitcnt lgkmcnt(0)
	v_mfma_f32_16x16x32_bf16 v[24:27], v[70:73], v[74:77], v[24:27]
	v_mfma_f32_16x16x32_bf16 v[20:23], v[70:73], v[78:81], v[20:23]
	v_mfma_f32_16x16x32_bf16 v[16:19], v[70:73], v[82:85], v[16:19]
	v_mfma_f32_16x16x32_bf16 v[12:15], v[70:73], v[86:89], v[12:15]
	ds_read_b128 v[70:73], v90 offset:22528
	ds_read_b128 v[90:93], v1 offset:6144
	s_waitcnt lgkmcnt(1)
	v_mfma_f32_16x16x32_bf16 v[8:11], v[70:73], v[74:77], v[8:11]
	v_mfma_f32_16x16x32_bf16 v[4:7], v[70:73], v[78:81], v[4:7]
	ds_read_b128 v[78:81], v1
	v_mfma_f32_16x16x32_bf16 v[74:77], v[70:73], v[82:85], v[48:51]
	ds_read_b128 v[82:85], v1 offset:2048
	s_nop 1
	ds_read_b128 v[48:51], v98 offset:16384
	v_mfma_f32_16x16x32_bf16 v[68:71], v[70:73], v[86:89], v[32:35]
	ds_read_b128 v[86:89], v1 offset:4096
	s_nop 1
	ds_read_b128 v[32:35], v98 offset:18432
	ds_read_b128 v[98:101], v98 offset:22528
	s_waitcnt lgkmcnt(3)
	v_mfma_f32_16x16x32_bf16 v[64:67], v[48:51], v[78:81], v[64:67]
	s_waitcnt vmcnt(0)
	s_waitcnt lgkmcnt(0)
	s_barrier
	v_mfma_f32_16x16x32_bf16 v[60:63], v[48:51], v[82:85], v[60:63]
	v_mfma_f32_16x16x32_bf16 v[56:59], v[48:51], v[86:89], v[56:59]
	v_mfma_f32_16x16x32_bf16 v[52:55], v[48:51], v[90:93], v[52:55]
	v_mfma_f32_16x16x32_bf16 v[48:51], v[32:35], v[78:81], v[44:47]
	v_mfma_f32_16x16x32_bf16 v[44:47], v[32:35], v[82:85], v[40:43]
	v_mfma_f32_16x16x32_bf16 v[40:43], v[32:35], v[86:89], v[36:39]
	v_mfma_f32_16x16x32_bf16 v[36:39], v[32:35], v[90:93], v[28:31]
	v_mfma_f32_16x16x32_bf16 v[32:35], v[94:97], v[78:81], v[24:27]
	v_mfma_f32_16x16x32_bf16 v[28:31], v[94:97], v[82:85], v[20:23]
	v_mfma_f32_16x16x32_bf16 v[24:27], v[94:97], v[86:89], v[16:19]
	v_mfma_f32_16x16x32_bf16 v[20:23], v[94:97], v[90:93], v[12:15]
	v_mfma_f32_16x16x32_bf16 v[16:19], v[98:101], v[78:81], v[8:11]
	v_mfma_f32_16x16x32_bf16 v[12:15], v[98:101], v[82:85], v[4:7]
	v_mfma_f32_16x16x32_bf16 v[8:11], v[98:101], v[86:89], v[74:77]
	v_mfma_f32_16x16x32_bf16 v[4:7], v[98:101], v[90:93], v[68:71]
	s_cbranch_scc0 .LBB0_143
	v_mov_b32_e32 v1, v168
	s_lshl_b32 s2, s44, 18
	v_readlane_b32 s18, v252, 26
	v_readlane_b32 s19, v252, 27
	v_ashrrev_i32_e32 v68, 3, v1
	s_add_u32 s2, s18, s2
	v_xor_b32_e32 v3, v68, v1
	v_ashrrev_i32_e32 v69, 31, v68
	s_addc_u32 s3, s19, 0
	v_lshlrev_b64 v[68:69], 11, v[68:69]
	v_lshlrev_b32_e32 v3, 4, v3
	v_lshlrev_b32_e32 v1, 4, v1
	v_lshl_add_u64 v[70:71], s[2:3], 0, v[68:69]
	v_and_b32_e32 v72, 0x70, v3
	v_mov_b32_e32 v73, v2
	v_readfirstlane_b32 s2, v1
	v_add_u32_e32 v3, 0x1000, v1
	s_lshl_b32 s20, s45, 18
	v_readlane_b32 s1, v252, 7
	v_lshl_add_u64 v[70:71], v[70:71], 0, v[72:73]
	s_mov_b32 m0, s2
	v_readfirstlane_b32 s2, v3
	v_add_u32_e32 v3, 0x2000, v1
	s_add_u32 s20, s1, s20
	v_readlane_b32 s1, v252, 8
	global_load_lds_dwordx4 v[70:71], off
	v_lshl_add_u64 v[74:75], v[70:71], 0, s[24:25]
	s_mov_b32 m0, s2
	v_readfirstlane_b32 s2, v3
	v_add_u32_e32 v3, 0x3000, v1
	s_addc_u32 s21, s1, 0
	global_load_lds_dwordx4 v[74:75], off
	v_lshl_add_u64 v[74:75], v[70:71], 0, s[26:27]
	s_mov_b32 m0, s2
	v_readfirstlane_b32 s2, v3
	v_add_u32_e32 v3, 0x4000, v1
	v_lshl_add_u64 v[68:69], s[20:21], 0, v[68:69]
	global_load_lds_dwordx4 v[74:75], off
	v_lshl_add_u64 v[70:71], v[70:71], 0, s[28:29]
	s_mov_b32 m0, s2
	v_readfirstlane_b32 s2, v3
	v_add_u32_e32 v3, 0x5000, v1
	global_load_lds_dwordx4 v[70:71], off
	v_lshl_add_u64 v[68:69], v[68:69], 0, v[72:73]
	s_mov_b32 m0, s2
	v_readfirstlane_b32 s2, v3
	v_add_u32_e32 v3, 0x6000, v1
	global_load_lds_dwordx4 v[68:69], off
	v_lshl_add_u64 v[70:71], v[68:69], 0, s[24:25]
	s_mov_b32 m0, s2
	v_readfirstlane_b32 s2, v3
	v_add_u32_e32 v1, 0x7000, v1
	global_load_lds_dwordx4 v[70:71], off
	v_lshl_add_u64 v[70:71], v[68:69], 0, s[26:27]
	s_mov_b32 m0, s2
	v_readfirstlane_b32 s2, v1
	global_load_lds_dwordx4 v[70:71], off
	v_lshl_add_u64 v[68:69], v[68:69], 0, s[28:29]
	s_mov_b32 m0, s2
	s_nop 0
	global_load_lds_dwordx4 v[68:69], off
	s_branch .LBB0_143

.LBB0_626:
	v_mov_b32_e32 v1, v168
	v_readlane_b32 s56, v254, 48
	v_readfirstlane_b32 s2, v1
	s_lshl_b32 s3, s2, 5
	s_lshl_b32 s2, s2, 6
	s_and_b32 s3, s3, 0xfffff000
	s_and_b32 s2, s2, 0x1000
	v_readlane_b32 s60, v254, 52
	v_lshrrev_b32_e32 v3, 4, v1
	v_and_b32_e32 v4, 7, v1
	v_lshlrev_b32_e32 v1, 6, v1
	v_readlane_b32 s61, v254, 53
	s_add_u32 s48, s60, s48
	v_bitop3_b32 v3, v3, v4, 3 bitop3:0x6c
	s_waitcnt vmcnt(0)
	v_and_b32_e32 v1, 0x3c0, v1
	s_addc_u32 s49, s61, s49
	v_lshlrev_b32_e32 v69, 3, v3
	v_or_b32_e32 v3, s3, v1
	v_or_b32_e32 v4, s2, v1
	s_add_u32 s50, s60, s50
	s_waitcnt lgkmcnt(0)
	v_mov_b32_e32 v32, 0
	v_xor_b32_e32 v1, 32, v69
	s_addc_u32 s51, s61, s51
	s_mov_b64 s[52:53], 0
	s_mov_b32 s41, 0
	v_lshlrev_b32_e32 v3, 1, v3
	v_lshlrev_b32_e32 v68, 1, v4
	v_mov_b32_e32 v33, v32
	v_mov_b32_e32 v34, v32
	v_mov_b32_e32 v35, v32
	v_mov_b32_e32 v48, v32
	v_mov_b32_e32 v49, v32
	v_mov_b32_e32 v50, v32
	v_mov_b32_e32 v51, v32
	v_mov_b32_e32 v4, v32
	v_mov_b32_e32 v5, v32
	v_mov_b32_e32 v6, v32
	v_mov_b32_e32 v7, v32
	v_mov_b32_e32 v8, v32
	v_mov_b32_e32 v9, v32
	v_mov_b32_e32 v10, v32
	v_mov_b32_e32 v11, v32
	v_mov_b32_e32 v12, v32
	v_mov_b32_e32 v13, v32
	v_mov_b32_e32 v14, v32
	v_mov_b32_e32 v15, v32
	v_mov_b32_e32 v16, v32
	v_mov_b32_e32 v17, v32
	v_mov_b32_e32 v18, v32
	v_mov_b32_e32 v19, v32
	v_mov_b32_e32 v20, v32
	v_mov_b32_e32 v21, v32
	v_mov_b32_e32 v22, v32
	v_mov_b32_e32 v23, v32
	v_mov_b32_e32 v24, v32
	v_mov_b32_e32 v25, v32
	v_mov_b32_e32 v26, v32
	v_mov_b32_e32 v27, v32
	v_mov_b32_e32 v28, v32
	v_mov_b32_e32 v29, v32
	v_mov_b32_e32 v30, v32
	v_mov_b32_e32 v31, v32
	v_mov_b32_e32 v36, v32
	v_mov_b32_e32 v37, v32
	v_mov_b32_e32 v38, v32
	v_mov_b32_e32 v39, v32
	v_mov_b32_e32 v40, v32
	v_mov_b32_e32 v41, v32
	v_mov_b32_e32 v42, v32
	v_mov_b32_e32 v43, v32
	v_mov_b32_e32 v44, v32
	v_mov_b32_e32 v45, v32
	v_mov_b32_e32 v46, v32
	v_mov_b32_e32 v47, v32
	v_mov_b32_e32 v52, v32
	v_mov_b32_e32 v53, v32
	v_mov_b32_e32 v54, v32
	v_mov_b32_e32 v55, v32
	v_mov_b32_e32 v56, v32
	v_mov_b32_e32 v57, v32
	v_mov_b32_e32 v58, v32
	v_mov_b32_e32 v59, v32
	v_mov_b32_e32 v60, v32
	v_mov_b32_e32 v61, v32
	v_mov_b32_e32 v62, v32
	v_mov_b32_e32 v63, v32
	v_mov_b32_e32 v64, v32
	v_mov_b32_e32 v65, v32
	v_mov_b32_e32 v66, v32
	v_mov_b32_e32 v67, v32
	s_waitcnt vmcnt(0)
	s_barrier
	v_readlane_b32 s57, v254, 49
	v_readlane_b32 s58, v254, 50
	v_readlane_b32 s59, v254, 51
	v_readlane_b32 s62, v254, 54
	v_readlane_b32 s63, v254, 55
	v_lshlrev_b32_e32 v86, 1, v69
	v_add_u32_e32 v160, v3, v86
	v_add_u32_e32 v162, v68, v86
	v_lshlrev_b32_e32 v86, 1, v1
	v_add_u32_e32 v161, v3, v86
	v_add_u32_e32 v163, v68, v86
	v_lshrrev_b32_e32 v87, 3, v168
	v_xor_b32_e32 v86, v87, v168
	v_and_b32_e32 v86, 7, v86
	v_lshlrev_b32_e32 v86, 4, v86
	s_movk_i32 s60, 0x800
	v_mad_u32_u24 v164, v87, s60, v86
	v_add_u32_e32 v165, 0x10000, v164
	v_add_u32_e32 v166, 0x20000, v164
	v_add_u32_e32 v167, 0x30000, v164
	s_add_u32 s56, s48, s68
	s_addc_u32 s57, s49, s69
	s_add_u32 s58, s50, 0x80080
	s_addc_u32 s59, s51, 0
	v_readfirstlane_b32 s60, v168
	s_lshl_b32 s60, s60, 4
	s_or_b32 s60, s60, 0x8000
	s_mov_b32 m0, s60
	s_nop 0
	global_load_lds_dwordx4 v164, s[56:57]
	s_add_u32 m0, s60, 0x1000
	s_nop 0
	global_load_lds_dwordx4 v165, s[56:57]
	s_add_u32 m0, s60, 0x2000
	s_nop 0
	global_load_lds_dwordx4 v166, s[56:57]
	s_add_u32 m0, s60, 0x3000
	s_nop 0
	global_load_lds_dwordx4 v167, s[56:57]
	s_add_u32 m0, s60, 0x4000
	s_nop 0
	global_load_lds_dwordx4 v164, s[58:59]
	s_add_u32 m0, s60, 0x5000
	s_nop 0
	global_load_lds_dwordx4 v165, s[58:59]
	s_add_u32 m0, s60, 0x6000
	s_nop 0
	global_load_lds_dwordx4 v166, s[58:59]
	s_add_u32 m0, s60, 0x7000
	s_nop 0
	global_load_lds_dwordx4 v167, s[58:59]
	s_add_u32 s56, s56, 0x80
	s_addc_u32 s57, s57, 0
	s_add_u32 s58, s58, 0x80
	s_addc_u32 s59, s59, 0
	s_xor_b32 s60, s60, 0x8000
.LBB0_627:
	s_waitcnt vmcnt(8)
	s_barrier
	ds_read_b128 v[70:73], v160
	ds_read_b128 v[74:77], v160 offset:2048
	ds_read_b128 v[78:81], v160 offset:4096
	ds_read_b128 v[82:85], v160 offset:6144
	ds_read_b128 v[112:115], v162 offset:16384
	ds_read_b128 v[116:119], v162 offset:18432
	ds_read_b128 v[120:123], v162 offset:20480
	ds_read_b128 v[124:127], v162 offset:22528
	ds_read_b128 v[128:131], v161
	ds_read_b128 v[132:135], v161 offset:2048
	ds_read_b128 v[136:139], v161 offset:4096
	ds_read_b128 v[140:143], v161 offset:6144
	ds_read_b128 v[144:147], v163 offset:16384
	ds_read_b128 v[148:151], v163 offset:18432
	ds_read_b128 v[152:155], v163 offset:20480
	s_waitcnt lgkmcnt(10)
	v_mfma_f32_16x16x32_bf16 v[64:67], v[112:115], v[70:73], v[64:67]
	v_mfma_f32_16x16x32_bf16 v[60:63], v[112:115], v[74:77], v[60:63]
	v_mfma_f32_16x16x32_bf16 v[56:59], v[112:115], v[78:81], v[56:59]
	v_mfma_f32_16x16x32_bf16 v[52:55], v[112:115], v[82:85], v[52:55]
	ds_read_b128 v[156:159], v163 offset:22528
	s_waitcnt lgkmcnt(10)
	v_mfma_f32_16x16x32_bf16 v[44:47], v[116:119], v[70:73], v[44:47]
	v_mfma_f32_16x16x32_bf16 v[40:43], v[116:119], v[74:77], v[40:43]
	v_mfma_f32_16x16x32_bf16 v[36:39], v[116:119], v[78:81], v[36:39]
	v_mfma_f32_16x16x32_bf16 v[28:31], v[116:119], v[82:85], v[28:31]
	v_xor_b32_e32 v160, 0x8000, v160
	v_xor_b32_e32 v162, 0x8000, v162
	s_waitcnt lgkmcnt(9)
	v_mfma_f32_16x16x32_bf16 v[24:27], v[120:123], v[70:73], v[24:27]
	v_mfma_f32_16x16x32_bf16 v[20:23], v[120:123], v[74:77], v[20:23]
	v_mfma_f32_16x16x32_bf16 v[16:19], v[120:123], v[78:81], v[16:19]
	v_mfma_f32_16x16x32_bf16 v[12:15], v[120:123], v[82:85], v[12:15]
	v_xor_b32_e32 v161, 0x8000, v161
	v_xor_b32_e32 v163, 0x8000, v163
	s_waitcnt lgkmcnt(8)
	v_mfma_f32_16x16x32_bf16 v[8:11], v[124:127], v[70:73], v[8:11]
	v_mfma_f32_16x16x32_bf16 v[4:7], v[124:127], v[74:77], v[4:7]
	v_mfma_f32_16x16x32_bf16 v[48:51], v[124:127], v[78:81], v[48:51]
	v_mfma_f32_16x16x32_bf16 v[32:35], v[124:127], v[82:85], v[32:35]
	s_waitcnt lgkmcnt(0)
	s_barrier
	s_cmp_eq_u32 s52, 0x700
	s_cbranch_scc1 .Lv3_nodma_G1
	s_mov_b32 m0, s60
	v_mfma_f32_16x16x32_bf16 v[64:67], v[144:147], v[128:131], v[64:67]
	global_load_lds_dwordx4 v164, s[56:57]
	s_add_u32 m0, s60, 0x1000
	v_mfma_f32_16x16x32_bf16 v[60:63], v[144:147], v[132:135], v[60:63]
	global_load_lds_dwordx4 v165, s[56:57]
	s_add_u32 m0, s60, 0x2000
	v_mfma_f32_16x16x32_bf16 v[56:59], v[144:147], v[136:139], v[56:59]
	global_load_lds_dwordx4 v166, s[56:57]
	s_add_u32 m0, s60, 0x3000
	v_mfma_f32_16x16x32_bf16 v[52:55], v[144:147], v[140:143], v[52:55]
	global_load_lds_dwordx4 v167, s[56:57]
	s_add_u32 m0, s60, 0x4000
	v_mfma_f32_16x16x32_bf16 v[44:47], v[148:151], v[128:131], v[44:47]
	global_load_lds_dwordx4 v164, s[58:59]
	s_add_u32 m0, s60, 0x5000
	v_mfma_f32_16x16x32_bf16 v[40:43], v[148:151], v[132:135], v[40:43]
	global_load_lds_dwordx4 v165, s[58:59]
	s_add_u32 m0, s60, 0x6000
	v_mfma_f32_16x16x32_bf16 v[36:39], v[148:151], v[136:139], v[36:39]
	global_load_lds_dwordx4 v166, s[58:59]
	s_add_u32 m0, s60, 0x7000
	v_mfma_f32_16x16x32_bf16 v[28:31], v[148:151], v[140:143], v[28:31]
	global_load_lds_dwordx4 v167, s[58:59]
	s_add_u32 s56, s56, 0x80
	s_addc_u32 s57, s57, 0
	s_add_u32 s58, s58, 0x80
	s_addc_u32 s59, s59, 0
	s_xor_b32 s60, s60, 0x8000
	s_branch .Lv3_join_G1

.Lv3_join_G1:
	s_add_u32 s52, s52, 0x80
	s_cmpk_eq_i32 s52, 0x780
	v_mfma_f32_16x16x32_bf16 v[24:27], v[152:155], v[128:131], v[24:27]
	v_mfma_f32_16x16x32_bf16 v[20:23], v[152:155], v[132:135], v[20:23]
	v_mfma_f32_16x16x32_bf16 v[16:19], v[152:155], v[136:139], v[16:19]
	v_mfma_f32_16x16x32_bf16 v[12:15], v[152:155], v[140:143], v[12:15]
	v_mfma_f32_16x16x32_bf16 v[8:11], v[156:159], v[128:131], v[8:11]
	v_mfma_f32_16x16x32_bf16 v[4:7], v[156:159], v[132:135], v[4:7]
	v_mfma_f32_16x16x32_bf16 v[48:51], v[156:159], v[136:139], v[48:51]
	v_mfma_f32_16x16x32_bf16 v[32:35], v[156:159], v[140:143], v[32:35]
	s_cbranch_scc0 .LBB0_627
	s_waitcnt vmcnt(0)
	s_barrier
	s_mov_b32 s37, 0x8000
	v_lshl_add_u32 v69, v69, 1, s37
	v_add_u32_e32 v90, v69, v68
	ds_read_b128 v[70:73], v90 offset:16384
	v_add_u32_e32 v69, v69, v3
	ds_read_b128 v[74:77], v69
	ds_read_b128 v[78:81], v69 offset:2048
	ds_read_b128 v[82:85], v69 offset:4096
	ds_read_b128 v[86:89], v69 offset:6144
	v_lshl_add_u32 v1, v1, 1, s37
	v_add_u32_e32 v98, v1, v68
	ds_read_b128 v[94:97], v98 offset:20480
	s_waitcnt lgkmcnt(4)
	v_mfma_f32_16x16x32_bf16 v[64:67], v[70:73], v[74:77], v[64:67]
	v_add_u32_e32 v1, v1, v3
	s_and_b64 vcc, exec, s[46:47]
	s_waitcnt lgkmcnt(3)
	v_mfma_f32_16x16x32_bf16 v[60:63], v[70:73], v[78:81], v[60:63]
	s_waitcnt lgkmcnt(2)
	v_mfma_f32_16x16x32_bf16 v[56:59], v[70:73], v[82:85], v[56:59]
	s_waitcnt lgkmcnt(1)
	v_mfma_f32_16x16x32_bf16 v[52:55], v[70:73], v[86:89], v[52:55]
	ds_read_b128 v[70:73], v90 offset:18432
	s_waitcnt lgkmcnt(0)
	v_mfma_f32_16x16x32_bf16 v[44:47], v[70:73], v[74:77], v[44:47]
	v_mfma_f32_16x16x32_bf16 v[40:43], v[70:73], v[78:81], v[40:43]
	v_mfma_f32_16x16x32_bf16 v[36:39], v[70:73], v[82:85], v[36:39]
	v_mfma_f32_16x16x32_bf16 v[28:31], v[70:73], v[86:89], v[28:31]
	ds_read_b128 v[70:73], v90 offset:20480
	s_waitcnt lgkmcnt(0)
	v_mfma_f32_16x16x32_bf16 v[24:27], v[70:73], v[74:77], v[24:27]
	v_mfma_f32_16x16x32_bf16 v[20:23], v[70:73], v[78:81], v[20:23]
	v_mfma_f32_16x16x32_bf16 v[16:19], v[70:73], v[82:85], v[16:19]
	v_mfma_f32_16x16x32_bf16 v[12:15], v[70:73], v[86:89], v[12:15]
	ds_read_b128 v[70:73], v90 offset:22528
	ds_read_b128 v[90:93], v1 offset:6144
	s_waitcnt lgkmcnt(1)
	v_mfma_f32_16x16x32_bf16 v[8:11], v[70:73], v[74:77], v[8:11]
	v_mfma_f32_16x16x32_bf16 v[4:7], v[70:73], v[78:81], v[4:7]
	ds_read_b128 v[78:81], v1
	v_mfma_f32_16x16x32_bf16 v[74:77], v[70:73], v[82:85], v[48:51]
	ds_read_b128 v[82:85], v1 offset:2048
	s_nop 1
	ds_read_b128 v[48:51], v98 offset:16384
	v_mfma_f32_16x16x32_bf16 v[68:71], v[70:73], v[86:89], v[32:35]
	ds_read_b128 v[86:89], v1 offset:4096
	s_nop 1
	ds_read_b128 v[32:35], v98 offset:18432
	s_waitcnt lgkmcnt(2)
	v_mfma_f32_16x16x32_bf16 v[64:67], v[48:51], v[78:81], v[64:67]
	v_mfma_f32_16x16x32_bf16 v[60:63], v[48:51], v[82:85], v[60:63]
	s_waitcnt lgkmcnt(1)
	v_mfma_f32_16x16x32_bf16 v[56:59], v[48:51], v[86:89], v[56:59]
	v_mfma_f32_16x16x32_bf16 v[52:55], v[48:51], v[90:93], v[52:55]
	s_waitcnt lgkmcnt(0)
	v_mfma_f32_16x16x32_bf16 v[48:51], v[32:35], v[78:81], v[44:47]
	v_mfma_f32_16x16x32_bf16 v[44:47], v[32:35], v[82:85], v[40:43]
	v_mfma_f32_16x16x32_bf16 v[40:43], v[32:35], v[86:89], v[36:39]
	v_mfma_f32_16x16x32_bf16 v[36:39], v[32:35], v[90:93], v[28:31]
	v_mfma_f32_16x16x32_bf16 v[32:35], v[94:97], v[78:81], v[24:27]
	v_mfma_f32_16x16x32_bf16 v[28:31], v[94:97], v[82:85], v[20:23]
	v_mfma_f32_16x16x32_bf16 v[24:27], v[94:97], v[86:89], v[16:19]
	v_mfma_f32_16x16x32_bf16 v[20:23], v[94:97], v[90:93], v[12:15]
	ds_read_b128 v[94:97], v98 offset:22528
	s_waitcnt vmcnt(0)
	s_waitcnt lgkmcnt(0)
	v_mfma_f32_16x16x32_bf16 v[16:19], v[94:97], v[78:81], v[8:11]
	s_barrier
	v_mfma_f32_16x16x32_bf16 v[12:15], v[94:97], v[82:85], v[4:7]
	v_mfma_f32_16x16x32_bf16 v[8:11], v[94:97], v[86:89], v[74:77]
	v_mfma_f32_16x16x32_bf16 v[4:7], v[94:97], v[90:93], v[68:71]
	s_cbranch_vccz .LBB0_630
	s_ashr_i32 s41, s40, 31
	v_mov_b32_e32 v1, v168
	s_lshl_b64 s[20:21], s[40:41], 18
	v_readlane_b32 s2, v252, 32
	v_readlane_b32 s3, v252, 33
	v_ashrrev_i32_e32 v68, 3, v1
	s_add_u32 s20, s2, s20
	v_xor_b32_e32 v3, v68, v1
	v_ashrrev_i32_e32 v69, 31, v68
	s_addc_u32 s21, s3, s21
	v_lshlrev_b64 v[68:69], 11, v[68:69]
	v_lshlrev_b32_e32 v3, 4, v3
	v_lshlrev_b32_e32 v1, 4, v1
	s_ashr_i32 s43, s42, 31
	v_lshl_add_u64 v[70:71], s[20:21], 0, v[68:69]
	v_and_b32_e32 v72, 0x70, v3
	v_mov_b32_e32 v73, v2
	v_readfirstlane_b32 s2, v1
	v_add_u32_e32 v3, 0x1000, v1
	s_lshl_b64 s[46:47], s[42:43], 18
	v_readlane_b32 s1, v252, 19
	v_lshl_add_u64 v[70:71], v[70:71], 0, v[72:73]
	s_mov_b32 m0, s2
	v_readfirstlane_b32 s2, v3
	v_add_u32_e32 v3, 0x2000, v1
	s_add_u32 s46, s1, s46
	v_readlane_b32 s1, v252, 20
	global_load_lds_dwordx4 v[70:71], off
	v_lshl_add_u64 v[74:75], v[70:71], 0, s[24:25]
	s_mov_b32 m0, s2
	v_readfirstlane_b32 s2, v3
	v_add_u32_e32 v3, 0x3000, v1
	s_addc_u32 s47, s1, s47
	global_load_lds_dwordx4 v[74:75], off
	v_lshl_add_u64 v[74:75], v[70:71], 0, s[26:27]
	s_mov_b32 m0, s2
	v_readfirstlane_b32 s2, v3
	v_add_u32_e32 v3, 0x4000, v1
	v_lshl_add_u64 v[68:69], s[46:47], 0, v[68:69]
	global_load_lds_dwordx4 v[74:75], off
	v_lshl_add_u64 v[70:71], v[70:71], 0, s[28:29]
	s_mov_b32 m0, s2
	v_readfirstlane_b32 s2, v3
	v_add_u32_e32 v3, 0x5000, v1
	global_load_lds_dwordx4 v[70:71], off
	v_lshl_add_u64 v[68:69], v[68:69], 0, v[72:73]
	s_mov_b32 m0, s2
	v_readfirstlane_b32 s2, v3
	v_add_u32_e32 v3, 0x6000, v1
	global_load_lds_dwordx4 v[68:69], off
	v_lshl_add_u64 v[70:71], v[68:69], 0, s[24:25]
	s_mov_b32 m0, s2
	v_readfirstlane_b32 s2, v3
	v_add_u32_e32 v1, 0x7000, v1
	global_load_lds_dwordx4 v[70:71], off
	v_lshl_add_u64 v[70:71], v[68:69], 0, s[26:27]
	s_mov_b32 m0, s2
	v_readfirstlane_b32 s2, v1
	global_load_lds_dwordx4 v[70:71], off
	v_lshl_add_u64 v[68:69], v[68:69], 0, s[28:29]
	s_mov_b32 m0, s2
	s_nop 0
	global_load_lds_dwordx4 v[68:69], off
